# v23 + cost-weighted spacing: one v_cvt_pk per PV MFMA gap instead of four in the last gap of each P fragment
# baseline (speedup 1.0000x reference)
.LBB0_1410:
	s_lshl_b32 s0, s70, 14
	s_add_i32 s0, s0, 0
	s_add_i32 s0, s0, 0x12000
	v_add_u32_e32 v16, s0, v163
	ds_read_b64_tr_b16 v[226:227], v16 offset:0
	ds_read_b64_tr_b16 v[228:229], v16 offset:2048
	v_add_u32_e32 v17, s0, v212
	ds_read_b64_tr_b16 v[230:231], v17 offset:0
	ds_read_b64_tr_b16 v[232:233], v17 offset:2048
	ds_read_b64_tr_b16 v[234:235], v16 offset:1024
	ds_read_b64_tr_b16 v[236:237], v16 offset:3072
	v_exp_f32_e32 v34, v34
	v_exp_f32_e32 v35, v35
	v_add_f32_e32 v220, v220, v34
	v_add_f32_e32 v220, v220, v35
	v_exp_f32_e32 v36, v36
	v_exp_f32_e32 v37, v37
	v_add_f32_e32 v220, v220, v36
	v_add_f32_e32 v220, v220, v37
	v_exp_f32_e32 v38, v38
	v_exp_f32_e32 v39, v39
	v_add_f32_e32 v220, v220, v38
	v_add_f32_e32 v220, v220, v39
	v_exp_f32_e32 v40, v40
	v_exp_f32_e32 v41, v41
	v_add_f32_e32 v220, v220, v40
	v_add_f32_e32 v220, v220, v41
	v_cvt_pk_bf16_f32 v4, v34, v35
	v_cvt_pk_bf16_f32 v5, v36, v37
	v_cvt_pk_bf16_f32 v6, v38, v39
	v_cvt_pk_bf16_f32 v7, v40, v41
	s_nop 1
	ds_read_b64_tr_b16 v[238:239], v17 offset:1024
	ds_read_b64_tr_b16 v[240:241], v17 offset:3072
	s_waitcnt lgkmcnt(6)
	v_mfma_f32_32x32x16_bf16 v[98:113], v[226:229], v[4:7], v[98:113]
	ds_read_b64_tr_b16 v[226:227], v16 offset:4096
	ds_read_b64_tr_b16 v[228:229], v16 offset:6144
	v_exp_f32_e32 v42, v42
	v_exp_f32_e32 v43, v43
	v_add_f32_e32 v220, v220, v42
	v_add_f32_e32 v220, v220, v43
	s_waitcnt lgkmcnt(6)
	v_mfma_f32_32x32x16_bf16 v[82:97], v[230:233], v[4:7], v[82:97]
	ds_read_b64_tr_b16 v[230:231], v17 offset:4096
	ds_read_b64_tr_b16 v[232:233], v17 offset:6144
	v_exp_f32_e32 v44, v44
	v_exp_f32_e32 v45, v45
	v_add_f32_e32 v220, v220, v44
	v_add_f32_e32 v220, v220, v45
	v_cvt_pk_bf16_f32 v8, v42, v43
	s_waitcnt lgkmcnt(6)
	v_mfma_f32_32x32x16_bf16 v[66:81], v[234:237], v[4:7], v[66:81]
	ds_read_b64_tr_b16 v[234:235], v16 offset:5120
	ds_read_b64_tr_b16 v[236:237], v16 offset:7168
	v_exp_f32_e32 v46, v46
	v_exp_f32_e32 v47, v47
	v_add_f32_e32 v220, v220, v46
	v_add_f32_e32 v220, v220, v47
	v_cvt_pk_bf16_f32 v9, v44, v45
	s_waitcnt lgkmcnt(6)
	v_mfma_f32_32x32x16_bf16 v[50:65], v[238:241], v[4:7], v[50:65]
	ds_read_b64_tr_b16 v[4:5], v17 offset:5120
	ds_read_b64_tr_b16 v[6:7], v17 offset:7168
	v_exp_f32_e32 v48, v48
	v_exp_f32_e32 v49, v49
	v_add_f32_e32 v220, v220, v48
	v_add_f32_e32 v220, v220, v49
	v_cvt_pk_bf16_f32 v10, v46, v47
	v_cvt_pk_bf16_f32 v11, v48, v49
	s_nop 1
	s_waitcnt lgkmcnt(6)
	v_mfma_f32_32x32x16_bf16 v[98:113], v[226:229], v[8:11], v[98:113]
	ds_read_b64_tr_b16 v[226:227], v16 offset:8192
	ds_read_b64_tr_b16 v[228:229], v16 offset:10240
	v_exp_f32_e32 v18, v18
	v_exp_f32_e32 v19, v19
	v_add_f32_e32 v220, v220, v18
	v_add_f32_e32 v220, v220, v19
	s_waitcnt lgkmcnt(6)
	v_mfma_f32_32x32x16_bf16 v[82:97], v[230:233], v[8:11], v[82:97]
	ds_read_b64_tr_b16 v[230:231], v17 offset:8192
	ds_read_b64_tr_b16 v[232:233], v17 offset:10240
	v_exp_f32_e32 v20, v20
	v_exp_f32_e32 v21, v21
	v_add_f32_e32 v220, v220, v20
	v_add_f32_e32 v220, v220, v21
	v_cvt_pk_bf16_f32 v12, v18, v19
	s_waitcnt lgkmcnt(6)
	v_mfma_f32_32x32x16_bf16 v[66:81], v[234:237], v[8:11], v[66:81]
	ds_read_b64_tr_b16 v[234:235], v16 offset:9216
	ds_read_b64_tr_b16 v[236:237], v16 offset:11264
	v_exp_f32_e32 v22, v22
	v_exp_f32_e32 v23, v23
	v_add_f32_e32 v220, v220, v22
	v_add_f32_e32 v220, v220, v23
	v_cvt_pk_bf16_f32 v13, v20, v21
	s_waitcnt lgkmcnt(6)
	v_mfma_f32_32x32x16_bf16 v[50:65], v[4:7], v[8:11], v[50:65]
	ds_read_b64_tr_b16 v[4:5], v17 offset:9216
	ds_read_b64_tr_b16 v[6:7], v17 offset:11264
	v_exp_f32_e32 v24, v24
	v_exp_f32_e32 v25, v25
	v_add_f32_e32 v220, v220, v24
	v_add_f32_e32 v220, v220, v25
	v_cvt_pk_bf16_f32 v14, v22, v23
	v_cvt_pk_bf16_f32 v15, v24, v25
	s_nop 1
	s_waitcnt lgkmcnt(6)
	v_mfma_f32_32x32x16_bf16 v[98:113], v[226:229], v[12:15], v[98:113]
	ds_read_b64_tr_b16 v[8:9], v16 offset:12288
	ds_read_b64_tr_b16 v[10:11], v16 offset:14336
	v_exp_f32_e32 v26, v26
	v_exp_f32_e32 v27, v27
	v_add_f32_e32 v220, v220, v26
	v_add_f32_e32 v220, v220, v27
	s_waitcnt lgkmcnt(6)
	v_mfma_f32_32x32x16_bf16 v[82:97], v[230:233], v[12:15], v[82:97]
	ds_read_b64_tr_b16 v[226:227], v17 offset:12288
	ds_read_b64_tr_b16 v[228:229], v17 offset:14336
	v_exp_f32_e32 v28, v28
	v_exp_f32_e32 v29, v29
	v_add_f32_e32 v220, v220, v28
	v_add_f32_e32 v220, v220, v29
	v_cvt_pk_bf16_f32 v222, v26, v27
	s_waitcnt lgkmcnt(6)
	v_mfma_f32_32x32x16_bf16 v[66:81], v[234:237], v[12:15], v[66:81]
	ds_read_b64_tr_b16 v[230:231], v16 offset:13312
	ds_read_b64_tr_b16 v[232:233], v16 offset:15360
	v_exp_f32_e32 v30, v30
	v_exp_f32_e32 v31, v31
	v_add_f32_e32 v220, v220, v30
	v_add_f32_e32 v220, v220, v31
	v_cvt_pk_bf16_f32 v223, v28, v29
	s_waitcnt lgkmcnt(6)
	v_mfma_f32_32x32x16_bf16 v[50:65], v[4:7], v[12:15], v[50:65]
	ds_read_b64_tr_b16 v[4:5], v17 offset:13312
	ds_read_b64_tr_b16 v[6:7], v17 offset:15360
	v_exp_f32_e32 v32, v32
	v_exp_f32_e32 v33, v33
	v_add_f32_e32 v220, v220, v32
	v_add_f32_e32 v220, v220, v33
	v_cvt_pk_bf16_f32 v224, v30, v31
	v_cvt_pk_bf16_f32 v225, v32, v33
	s_nop 1
	s_waitcnt lgkmcnt(6)
	v_mfma_f32_32x32x16_bf16 v[98:113], v[8:11], v[222:225], v[98:113]
	s_waitcnt lgkmcnt(4)
	v_mfma_f32_32x32x16_bf16 v[82:97], v[226:229], v[222:225], v[82:97]
	s_waitcnt lgkmcnt(2)
	v_mfma_f32_32x32x16_bf16 v[66:81], v[230:233], v[222:225], v[66:81]
	s_waitcnt lgkmcnt(0)
	v_mfma_f32_32x32x16_bf16 v[50:65], v[4:7], v[222:225], v[50:65]
